# v11 + K-loop: the loader's two waits before the pre-MMA barrier merged into one s_waitcnt
# baseline (speedup 1.0000x reference)
.LBB0_344:
	s_add_i32 s4, s2, 2
	s_add_u32 s5, s68, s0
	s_addc_u32 s3, s69, s1
	s_add_u32 s33, s86, s0
	s_addc_u32 s35, s87, s1
	s_add_i32 s47, 0, 0x10000
	s_cmp_eq_u32 s21, s2
	s_cselect_b32 s3, s65, s3
	s_cselect_b32 s2, s64, s5
	v_add_u32_e32 v17, s47, v237
	s_cselect_b32 s57, s67, s35
	s_cselect_b32 s56, s66, s33
	s_add_i32 s5, 0, 0x14000
	ds_read_b128 v[134:137], v17
	ds_read_b128 v[138:141], v17 offset:1024
	ds_read_b128 v[142:145], v17 offset:2048
	ds_read_b128 v[146:149], v17 offset:3072
	v_add_u32_e32 v17, s5, v237
	ds_read_b128 v[150:153], v17
	ds_read_b128 v[154:157], v17 offset:1024
	ds_read_b128 v[158:161], v17 offset:2048
	ds_read_b128 v[162:165], v17 offset:3072
	v_lshl_add_u64 v[170:171], s[68:69], 0, v[132:133]
	s_add_i32 m0, s37, 0xc000
	ds_read_b128 v[166:169], v240
	ds_read_b128 v[186:189], v240 offset:1024
	ds_read_b128 v[190:193], v240 offset:2048
	ds_read_b128 v[194:197], v240 offset:3072
	ds_read_b128 v[198:201], v240 offset:4096
	ds_read_b128 v[202:205], v240 offset:5120
	ds_read_b128 v[206:209], v240 offset:6144
	ds_read_b128 v[210:213], v240 offset:7168
	global_load_lds_dwordx4 v[170:171], off
	v_lshl_add_u64 v[170:171], s[68:69], 0, v[18:19]
	s_add_i32 m0, s37, 0xe000
	s_nop 0
	global_load_lds_dwordx4 v[170:171], off
	s_waitcnt vmcnt(8) lgkmcnt(0)
	s_setprio 1
	s_barrier
	v_mfma_f32_16x16x32_bf16 v[8:11], v[134:137], v[166:169], v[8:11]
	v_mfma_f32_16x16x32_bf16 v[12:15], v[142:145], v[166:169], v[12:15]
	v_mfma_f32_16x16x32_bf16 v[28:31], v[134:137], v[190:193], v[28:31]
	v_mfma_f32_16x16x32_bf16 v[32:35], v[142:145], v[190:193], v[32:35]
	v_mfma_f32_16x16x32_bf16 v[36:39], v[134:137], v[198:201], v[36:39]
	v_mfma_f32_16x16x32_bf16 v[44:47], v[142:145], v[198:201], v[44:47]
	v_mfma_f32_16x16x32_bf16 v[80:83], v[134:137], v[206:209], v[80:83]
	v_mfma_f32_16x16x32_bf16 v[88:91], v[142:145], v[206:209], v[88:91]
	v_mfma_f32_16x16x32_bf16 v[8:11], v[138:141], v[186:189], v[8:11]
	v_mfma_f32_16x16x32_bf16 v[12:15], v[146:149], v[186:189], v[12:15]
	v_mfma_f32_16x16x32_bf16 v[28:31], v[138:141], v[194:197], v[28:31]
	v_mfma_f32_16x16x32_bf16 v[32:35], v[146:149], v[194:197], v[32:35]
	v_mfma_f32_16x16x32_bf16 v[36:39], v[138:141], v[202:205], v[36:39]
	v_mfma_f32_16x16x32_bf16 v[44:47], v[146:149], v[202:205], v[44:47]
	v_mfma_f32_16x16x32_bf16 v[80:83], v[138:141], v[210:213], v[80:83]
	v_mfma_f32_16x16x32_bf16 v[88:91], v[146:149], v[210:213], v[88:91]
	v_mfma_f32_16x16x32_bf16 v[0:3], v[150:153], v[166:169], v[0:3]
	v_mfma_f32_16x16x32_bf16 v[4:7], v[158:161], v[166:169], v[4:7]
	v_mfma_f32_16x16x32_bf16 v[20:23], v[150:153], v[190:193], v[20:23]
	v_mfma_f32_16x16x32_bf16 v[24:27], v[158:161], v[190:193], v[24:27]
	v_mfma_f32_16x16x32_bf16 v[40:43], v[150:153], v[198:201], v[40:43]
	v_mfma_f32_16x16x32_bf16 v[48:51], v[158:161], v[198:201], v[48:51]
	v_mfma_f32_16x16x32_bf16 v[60:63], v[150:153], v[206:209], v[60:63]
	v_mfma_f32_16x16x32_bf16 v[64:67], v[158:161], v[206:209], v[64:67]
	v_mfma_f32_16x16x32_bf16 v[0:3], v[154:157], v[186:189], v[0:3]
	v_mfma_f32_16x16x32_bf16 v[4:7], v[162:165], v[186:189], v[4:7]
	v_mfma_f32_16x16x32_bf16 v[20:23], v[154:157], v[194:197], v[20:23]
	v_mfma_f32_16x16x32_bf16 v[24:27], v[162:165], v[194:197], v[24:27]
	v_mfma_f32_16x16x32_bf16 v[40:43], v[154:157], v[202:205], v[40:43]
	v_mfma_f32_16x16x32_bf16 v[48:51], v[162:165], v[202:205], v[48:51]
	v_mfma_f32_16x16x32_bf16 v[60:63], v[154:157], v[210:213], v[60:63]
	v_mfma_f32_16x16x32_bf16 v[64:67], v[162:165], v[210:213], v[64:67]
	s_barrier
	s_setprio 0
	s_add_i32 s33, s47, s17
	v_lshl_add_u64 v[170:171], s[56:57], 0, v[174:175]
	s_mov_b32 m0, s33
	ds_read_b128 v[166:169], v240 offset:16384
	ds_read_b128 v[186:189], v240 offset:17408
	ds_read_b128 v[190:193], v240 offset:18432
	ds_read_b128 v[194:197], v240 offset:19456
	ds_read_b128 v[198:201], v240 offset:20480
	ds_read_b128 v[202:205], v240 offset:21504
	ds_read_b128 v[206:209], v240 offset:22528
	ds_read_b128 v[210:213], v240 offset:23552
	global_load_lds_dwordx4 v[170:171], off
	s_add_i32 m0, s33, 0x2000
	v_lshl_add_u64 v[214:215], s[56:57], 0, v[178:179]
	s_add_u32 s56, s56, s36
	s_addc_u32 s57, s57, 0
	s_add_i32 s5, s5, s17
	global_load_lds_dwordx4 v[214:215], off
	v_lshl_add_u64 v[216:217], s[56:57], 0, v[174:175]
	s_mov_b32 m0, s5
	v_lshl_add_u64 v[224:225], s[56:57], 0, v[178:179]
	global_load_lds_dwordx4 v[216:217], off
	s_add_i32 m0, s5, 0x2000
	v_lshl_add_u64 v[226:227], s[2:3], 0, v[172:173]
	global_load_lds_dwordx4 v[224:225], off
	s_mov_b32 m0, s37
	v_lshl_add_u64 v[242:243], s[2:3], 0, v[176:177]
	global_load_lds_dwordx4 v[226:227], off
	s_mov_b32 m0, s45
	s_nop 0
	global_load_lds_dwordx4 v[242:243], off
	s_waitcnt vmcnt(8) lgkmcnt(0)
	s_setprio 1
	s_barrier
	v_mfma_f32_16x16x32_bf16 v[68:71], v[134:137], v[166:169], v[68:71]
	v_mfma_f32_16x16x32_bf16 v[72:75], v[142:145], v[166:169], v[72:75]
	v_mfma_f32_16x16x32_bf16 v[92:95], v[134:137], v[190:193], v[92:95]
	v_mfma_f32_16x16x32_bf16 v[96:99], v[142:145], v[190:193], v[96:99]
	v_mfma_f32_16x16x32_bf16 v[108:111], v[134:137], v[198:201], v[108:111]
	v_mfma_f32_16x16x32_bf16 v[112:115], v[142:145], v[198:201], v[112:115]
	v_mfma_f32_16x16x32_bf16 v[124:127], v[134:137], v[206:209], v[124:127]
	v_mfma_f32_16x16x32_bf16 v[128:131], v[142:145], v[206:209], v[128:131]
	v_mfma_f32_16x16x32_bf16 v[68:71], v[138:141], v[186:189], v[68:71]
	v_mfma_f32_16x16x32_bf16 v[72:75], v[146:149], v[186:189], v[72:75]
	v_mfma_f32_16x16x32_bf16 v[92:95], v[138:141], v[194:197], v[92:95]
	v_mfma_f32_16x16x32_bf16 v[96:99], v[146:149], v[194:197], v[96:99]
	v_mfma_f32_16x16x32_bf16 v[108:111], v[138:141], v[202:205], v[108:111]
	v_mfma_f32_16x16x32_bf16 v[112:115], v[146:149], v[202:205], v[112:115]
	v_mfma_f32_16x16x32_bf16 v[124:127], v[138:141], v[210:213], v[124:127]
	v_mfma_f32_16x16x32_bf16 v[128:131], v[146:149], v[210:213], v[128:131]
	v_mfma_f32_16x16x32_bf16 v[52:55], v[150:153], v[166:169], v[52:55]
	v_mfma_f32_16x16x32_bf16 v[56:59], v[158:161], v[166:169], v[56:59]
	v_mfma_f32_16x16x32_bf16 v[76:79], v[150:153], v[190:193], v[76:79]
	v_mfma_f32_16x16x32_bf16 v[84:87], v[158:161], v[190:193], v[84:87]
	v_mfma_f32_16x16x32_bf16 v[100:103], v[150:153], v[198:201], v[100:103]
	v_mfma_f32_16x16x32_bf16 v[104:107], v[158:161], v[198:201], v[104:107]
	v_mfma_f32_16x16x32_bf16 v[116:119], v[150:153], v[206:209], v[116:119]
	v_mfma_f32_16x16x32_bf16 v[120:123], v[158:161], v[206:209], v[120:123]
	v_mfma_f32_16x16x32_bf16 v[52:55], v[154:157], v[186:189], v[52:55]
	v_mfma_f32_16x16x32_bf16 v[56:59], v[162:165], v[186:189], v[56:59]
	v_mfma_f32_16x16x32_bf16 v[76:79], v[154:157], v[194:197], v[76:79]
	v_mfma_f32_16x16x32_bf16 v[84:87], v[162:165], v[194:197], v[84:87]
	v_mfma_f32_16x16x32_bf16 v[100:103], v[154:157], v[202:205], v[100:103]
	v_mfma_f32_16x16x32_bf16 v[104:107], v[162:165], v[202:205], v[104:107]
	v_mfma_f32_16x16x32_bf16 v[116:119], v[154:157], v[210:213], v[116:119]
	v_mfma_f32_16x16x32_bf16 v[120:123], v[162:165], v[210:213], v[120:123]
	s_barrier
	s_setprio 0
	s_add_i32 s5, 0, 0x18000
	v_add_u32_e32 v17, s5, v237
	s_add_i32 s33, 0, 0x1c000
	ds_read_b128 v[134:137], v17
	ds_read_b128 v[138:141], v17 offset:1024
	ds_read_b128 v[142:145], v17 offset:2048
	ds_read_b128 v[146:149], v17 offset:3072
	v_add_u32_e32 v17, s33, v237
	ds_read_b128 v[150:153], v17
	ds_read_b128 v[154:157], v17 offset:1024
	ds_read_b128 v[158:161], v17 offset:2048
	ds_read_b128 v[162:165], v17 offset:3072
	s_add_u32 s2, s2, s36
	s_addc_u32 s3, s3, 0
	s_mov_b32 m0, s26
	v_lshl_add_u64 v[244:245], s[2:3], 0, v[172:173]
	ds_read_b128 v[166:169], v240 offset:32768
	ds_read_b128 v[186:189], v240 offset:33792
	ds_read_b128 v[190:193], v240 offset:34816
	ds_read_b128 v[194:197], v240 offset:35840
	ds_read_b128 v[198:201], v240 offset:36864
	ds_read_b128 v[202:205], v240 offset:37888
	ds_read_b128 v[206:209], v240 offset:38912
	ds_read_b128 v[210:213], v240 offset:39936
	global_load_lds_dwordx4 v[244:245], off
	v_lshl_add_u64 v[244:245], s[2:3], 0, v[176:177]
	s_mov_b32 m0, s27
	s_nop 0
	global_load_lds_dwordx4 v[244:245], off
	s_waitcnt vmcnt(8) lgkmcnt(0)
	s_setprio 1
	s_barrier
	v_mfma_f32_16x16x32_bf16 v[8:11], v[134:137], v[166:169], v[8:11]
	v_mfma_f32_16x16x32_bf16 v[12:15], v[142:145], v[166:169], v[12:15]
	v_mfma_f32_16x16x32_bf16 v[28:31], v[134:137], v[190:193], v[28:31]
	v_mfma_f32_16x16x32_bf16 v[32:35], v[142:145], v[190:193], v[32:35]
	v_mfma_f32_16x16x32_bf16 v[36:39], v[134:137], v[198:201], v[36:39]
	v_mfma_f32_16x16x32_bf16 v[44:47], v[142:145], v[198:201], v[44:47]
	v_mfma_f32_16x16x32_bf16 v[80:83], v[134:137], v[206:209], v[80:83]
	v_mfma_f32_16x16x32_bf16 v[88:91], v[142:145], v[206:209], v[88:91]
	v_mfma_f32_16x16x32_bf16 v[8:11], v[138:141], v[186:189], v[8:11]
	v_mfma_f32_16x16x32_bf16 v[12:15], v[146:149], v[186:189], v[12:15]
	v_mfma_f32_16x16x32_bf16 v[28:31], v[138:141], v[194:197], v[28:31]
	v_mfma_f32_16x16x32_bf16 v[32:35], v[146:149], v[194:197], v[32:35]
	v_mfma_f32_16x16x32_bf16 v[36:39], v[138:141], v[202:205], v[36:39]
	v_mfma_f32_16x16x32_bf16 v[44:47], v[146:149], v[202:205], v[44:47]
	v_mfma_f32_16x16x32_bf16 v[80:83], v[138:141], v[210:213], v[80:83]
	v_mfma_f32_16x16x32_bf16 v[88:91], v[146:149], v[210:213], v[88:91]
	v_mfma_f32_16x16x32_bf16 v[0:3], v[150:153], v[166:169], v[0:3]
	v_mfma_f32_16x16x32_bf16 v[4:7], v[158:161], v[166:169], v[4:7]
	v_mfma_f32_16x16x32_bf16 v[20:23], v[150:153], v[190:193], v[20:23]
	v_mfma_f32_16x16x32_bf16 v[24:27], v[158:161], v[190:193], v[24:27]
	v_mfma_f32_16x16x32_bf16 v[40:43], v[150:153], v[198:201], v[40:43]
	v_mfma_f32_16x16x32_bf16 v[48:51], v[158:161], v[198:201], v[48:51]
	v_mfma_f32_16x16x32_bf16 v[60:63], v[150:153], v[206:209], v[60:63]
	v_mfma_f32_16x16x32_bf16 v[64:67], v[158:161], v[206:209], v[64:67]
	v_mfma_f32_16x16x32_bf16 v[0:3], v[154:157], v[186:189], v[0:3]
	v_mfma_f32_16x16x32_bf16 v[4:7], v[162:165], v[186:189], v[4:7]
	v_mfma_f32_16x16x32_bf16 v[20:23], v[154:157], v[194:197], v[20:23]
	v_mfma_f32_16x16x32_bf16 v[24:27], v[162:165], v[194:197], v[24:27]
	v_mfma_f32_16x16x32_bf16 v[40:43], v[154:157], v[202:205], v[40:43]
	v_mfma_f32_16x16x32_bf16 v[48:51], v[162:165], v[202:205], v[48:51]
	v_mfma_f32_16x16x32_bf16 v[60:63], v[154:157], v[210:213], v[60:63]
	v_mfma_f32_16x16x32_bf16 v[64:67], v[162:165], v[210:213], v[64:67]
	s_barrier
	s_setprio 0
	s_add_i32 s2, s5, s17
	v_lshl_add_u64 v[170:171], v[170:171], 0, s[6:7]
	s_mov_b32 m0, s2
	ds_read_b128 v[166:169], v240 offset:49152
	ds_read_b128 v[186:189], v240 offset:50176
	ds_read_b128 v[190:193], v240 offset:51200
	ds_read_b128 v[194:197], v240 offset:52224
	ds_read_b128 v[198:201], v240 offset:53248
	ds_read_b128 v[202:205], v240 offset:54272
	ds_read_b128 v[206:209], v240 offset:55296
	ds_read_b128 v[210:213], v240 offset:56320
	global_load_lds_dwordx4 v[170:171], off
	v_lshl_add_u64 v[170:171], v[214:215], 0, s[6:7]
	s_add_i32 m0, s2, 0x2000
	s_add_i32 s2, s33, s17
	global_load_lds_dwordx4 v[170:171], off
	v_lshl_add_u64 v[170:171], v[216:217], 0, s[6:7]
	s_mov_b32 m0, s2
	s_nop 0
	global_load_lds_dwordx4 v[170:171], off
	v_lshl_add_u64 v[170:171], v[224:225], 0, s[6:7]
	s_add_i32 m0, s2, 0x2000
	s_nop 0
	global_load_lds_dwordx4 v[170:171], off
	v_lshl_add_u64 v[170:171], v[226:227], 0, s[6:7]
	s_mov_b32 m0, s63
	s_nop 0
	global_load_lds_dwordx4 v[170:171], off
	v_lshl_add_u64 v[170:171], v[242:243], 0, s[6:7]
	s_mov_b32 m0, s20
	s_nop 0
	global_load_lds_dwordx4 v[170:171], off
	s_waitcnt vmcnt(8) lgkmcnt(0)
	s_setprio 1
	s_barrier
	v_mfma_f32_16x16x32_bf16 v[68:71], v[134:137], v[166:169], v[68:71]
	v_mfma_f32_16x16x32_bf16 v[72:75], v[142:145], v[166:169], v[72:75]
	v_mfma_f32_16x16x32_bf16 v[92:95], v[134:137], v[190:193], v[92:95]
	v_mfma_f32_16x16x32_bf16 v[96:99], v[142:145], v[190:193], v[96:99]
	v_mfma_f32_16x16x32_bf16 v[108:111], v[134:137], v[198:201], v[108:111]
	v_mfma_f32_16x16x32_bf16 v[112:115], v[142:145], v[198:201], v[112:115]
	v_mfma_f32_16x16x32_bf16 v[124:127], v[134:137], v[206:209], v[124:127]
	v_mfma_f32_16x16x32_bf16 v[128:131], v[142:145], v[206:209], v[128:131]
	v_mfma_f32_16x16x32_bf16 v[68:71], v[138:141], v[186:189], v[68:71]
	v_mfma_f32_16x16x32_bf16 v[72:75], v[146:149], v[186:189], v[72:75]
	v_mfma_f32_16x16x32_bf16 v[92:95], v[138:141], v[194:197], v[92:95]
	v_mfma_f32_16x16x32_bf16 v[96:99], v[146:149], v[194:197], v[96:99]
	v_mfma_f32_16x16x32_bf16 v[108:111], v[138:141], v[202:205], v[108:111]
	v_mfma_f32_16x16x32_bf16 v[112:115], v[146:149], v[202:205], v[112:115]
	v_mfma_f32_16x16x32_bf16 v[124:127], v[138:141], v[210:213], v[124:127]
	v_mfma_f32_16x16x32_bf16 v[128:131], v[146:149], v[210:213], v[128:131]
	v_mfma_f32_16x16x32_bf16 v[52:55], v[150:153], v[166:169], v[52:55]
	v_mfma_f32_16x16x32_bf16 v[56:59], v[158:161], v[166:169], v[56:59]
	v_mfma_f32_16x16x32_bf16 v[76:79], v[150:153], v[190:193], v[76:79]
	v_mfma_f32_16x16x32_bf16 v[84:87], v[158:161], v[190:193], v[84:87]
	v_mfma_f32_16x16x32_bf16 v[100:103], v[150:153], v[198:201], v[100:103]
	v_mfma_f32_16x16x32_bf16 v[104:107], v[158:161], v[198:201], v[104:107]
	v_mfma_f32_16x16x32_bf16 v[116:119], v[150:153], v[206:209], v[116:119]
	v_mfma_f32_16x16x32_bf16 v[120:123], v[158:161], v[206:209], v[120:123]
	v_mfma_f32_16x16x32_bf16 v[52:55], v[154:157], v[186:189], v[52:55]
	v_mfma_f32_16x16x32_bf16 v[56:59], v[162:165], v[186:189], v[56:59]
	v_mfma_f32_16x16x32_bf16 v[76:79], v[154:157], v[194:197], v[76:79]
	v_mfma_f32_16x16x32_bf16 v[84:87], v[162:165], v[194:197], v[84:87]
	v_mfma_f32_16x16x32_bf16 v[100:103], v[154:157], v[202:205], v[100:103]
	v_mfma_f32_16x16x32_bf16 v[104:107], v[162:165], v[202:205], v[104:107]
	v_mfma_f32_16x16x32_bf16 v[116:119], v[154:157], v[210:213], v[116:119]
	v_mfma_f32_16x16x32_bf16 v[120:123], v[162:165], v[210:213], v[120:123]
	s_barrier
	s_setprio 0
	s_add_u32 s0, s0, 0x100
	s_addc_u32 s1, s1, 0
	v_lshl_add_u64 v[132:133], v[132:133], 0, s[8:9]
	v_lshl_add_u64 v[18:19], v[18:19], 0, s[8:9]
	s_cmp_ge_u32 s4, s62
	s_mov_b32 s2, s4
	s_cbranch_scc0 .LBB0_344
	v_readlane_b32 s0, v253, 40
	v_readlane_b32 s1, v253, 41
	s_and_b64 vcc, exec, s[0:1]
	s_cbranch_vccz .LBB0_347
	s_barrier
